# grid barrier poll loop keeps two sc1 polls in flight (no s_sleep), poll results land in otherwise unused VGPRs
# speedup vs baseline: 1.0808x; 1.0015x over previous
.Lxb_poll_0:
	v_readlane_b32 s8, v255, 12
	v_readlane_b32 s9, v255, 13
	s_nop 4
	buffer_inv sc1
	global_load_dword v249, v193, s[8:9] sc1
.Lxb_spin_0:
	global_load_dword v250, v193, s[8:9] sc1
	s_waitcnt vmcnt(1)
	v_cmp_lt_u32_e32 vcc, v249, v3
	s_cbranch_vccz .Lxb_done_0
	global_load_dword v249, v193, s[8:9] sc1
	s_waitcnt vmcnt(1)
	v_cmp_lt_u32_e32 vcc, v250, v3
	s_cbranch_vccz .Lxb_done_0
	s_branch .Lxb_spin_0
